# speedup vs baseline: 1.0073x; 1.0073x over previous
.LBB0_212:
	s_andn2_b64 vcc, exec, s[82:83]
	s_waitcnt lgkmcnt(0)
	s_barrier
	s_cbranch_vccnz .LBB0_161
	ds_read2_b32 v[98:99], v163 offset1:32
	ds_read2_b32 v[102:103], v163 offset0:64 offset1:96
	v_mov_b32_e32 v100, v50
	v_mov_b32_e32 v101, v34
	v_mov_b32_e32 v104, v18
	s_waitcnt lgkmcnt(1)
	v_pk_fma_f32 v[98:99], v[100:101], v[96:97], v[98:99] op_sel_hi:[1,0,1] neg_lo:[0,0,1] neg_hi:[0,0,1]
	v_mov_b32_e32 v105, v2
	v_pk_mul_f32 v[100:101], v[98:99], v[98:99]
	s_waitcnt lgkmcnt(0)
	v_pk_fma_f32 v[96:97], v[104:105], v[96:97], v[102:103] op_sel_hi:[1,0,1] neg_lo:[0,0,1] neg_hi:[0,0,1]
	v_add_f32_e32 v1, v100, v101
	v_pk_mul_f32 v[102:103], v[96:97], v[96:97]
	s_ashr_i32 s8, s74, 31
	v_add_f32_e32 v1, v1, v102
	v_add_f32_e32 v1, v1, v103
	s_add_u32 s10, s86, s74
	s_addc_u32 s11, s87, s8
	v_mov_b32_e32 v101, s11
	v_or_b32_e32 v100, s10, v130
	s_waitcnt lgkmcnt(0)
	s_nop 1
	v_add_f32_dpp v1, v1, v1 quad_perm:[1,0,3,2] row_mask:0xf bank_mask:0xf
	v_lshlrev_b64 v[100:101], 11, v[100:101]
	v_lshl_add_u64 v[100:101], v[196:197], 0, v[100:101]
	s_waitcnt lgkmcnt(0)
	s_nop 1
	v_add_f32_dpp v1, v1, v1 quad_perm:[2,3,0,1] row_mask:0xf bank_mask:0xf
	s_waitcnt lgkmcnt(0)
	s_nop 1
	v_add_f32_dpp v1, v1, v1 row_half_mirror row_mask:0xf bank_mask:0xf
	s_waitcnt lgkmcnt(0)
	s_nop 1
	v_add_f32_dpp v1, v1, v1 row_mirror row_mask:0xf bank_mask:0xf
	ds_bpermute_b32 v2, v147, v1
	s_waitcnt lgkmcnt(0)
	v_add_f32_e32 v1, v1, v2
	v_fmamk_f32 v1, v1, 0x3c000000, v208
	v_cmp_gt_f32_e32 vcc, s95, v1
	v_mul_f32_e32 v2, 0x4b800000, v1
	s_nop 0
	v_cndmask_b32_e32 v1, v1, v2, vcc
	v_rsq_f32_e32 v1, v1
	s_nop 0
	v_mul_f32_e32 v2, 0x45800000, v1
	v_cndmask_b32_e32 v1, v1, v2, vcc
	v_mul_f32_e32 v2, v98, v1
	s_nop 1
	v_mov_b32_dpp v18, v2 quad_perm:[1,0,3,2] row_mask:0xf bank_mask:0xf
	s_and_saveexec_b64 s[8:9], s[6:7]
	s_cbranch_execz .LBB0_215
	s_waitcnt lgkmcnt(0)
	v_cvt_pk_bf16_f32 v2, v2, v18
	global_store_dword v[100:101], v2, off
.LBB0_215:
	s_or_b64 exec, exec, s[8:9]
	v_mul_f32_e32 v2, v99, v1
	s_waitcnt lgkmcnt(0)
	s_nop 1
	v_mov_b32_dpp v18, v2 quad_perm:[1,0,3,2] row_mask:0xf bank_mask:0xf
	s_and_saveexec_b64 s[8:9], s[6:7]
	s_cbranch_execz .LBB0_217
	s_waitcnt lgkmcnt(0)
	v_cvt_pk_bf16_f32 v2, v2, v18
	global_store_dword v[100:101], v2, off offset:64
.LBB0_217:
	s_or_b64 exec, exec, s[8:9]
	v_mul_f32_e32 v2, v96, v1
	s_waitcnt lgkmcnt(0)
	s_nop 1
	v_mov_b32_dpp v18, v2 quad_perm:[1,0,3,2] row_mask:0xf bank_mask:0xf
	s_and_saveexec_b64 s[8:9], s[6:7]
	s_cbranch_execz .LBB0_219
	s_waitcnt lgkmcnt(0)
	v_cvt_pk_bf16_f32 v2, v2, v18
	global_store_dword v[100:101], v2, off offset:128
.LBB0_219:
	s_or_b64 exec, exec, s[8:9]
	v_mul_f32_e32 v1, v97, v1
	s_nop 1
	v_mov_b32_dpp v2, v1 quad_perm:[1,0,3,2] row_mask:0xf bank_mask:0xf
	s_and_saveexec_b64 s[8:9], s[6:7]
	s_cbranch_execz .LBB0_221
	s_waitcnt lgkmcnt(0)
	v_cvt_pk_bf16_f32 v1, v1, v2
	global_store_dword v[100:101], v1, off offset:192
.LBB0_221:
	s_or_b64 exec, exec, s[8:9]
	ds_read2_b32 v[96:97], v165 offset1:32
	ds_read2_b32 v[98:99], v165 offset0:64 offset1:96
	v_mov_b32_e32 v34, v51
	s_waitcnt lgkmcnt(2)
	v_mov_b32_e32 v2, v19
	s_waitcnt lgkmcnt(1)
	v_pk_fma_f32 v[18:19], v[34:35], v[94:95], v[96:97] op_sel_hi:[1,0,1] neg_lo:[0,0,1] neg_hi:[0,0,1]
	s_waitcnt lgkmcnt(0)
	v_pk_fma_f32 v[2:3], v[2:3], v[94:95], v[98:99] op_sel_hi:[1,0,1] neg_lo:[0,0,1] neg_hi:[0,0,1]
	v_pk_mul_f32 v[34:35], v[18:19], v[18:19]
	v_pk_mul_f32 v[50:51], v[2:3], v[2:3]
	v_add_f32_e32 v1, v34, v35
	v_add_f32_e32 v1, v1, v50
	v_add_f32_e32 v1, v1, v51
	v_mov_b32_e32 v35, s11
	s_waitcnt lgkmcnt(0)
	s_nop 1
	v_add_f32_dpp v1, v1, v1 quad_perm:[1,0,3,2] row_mask:0xf bank_mask:0xf
	s_waitcnt lgkmcnt(0)
	s_nop 1
	v_add_f32_dpp v1, v1, v1 quad_perm:[2,3,0,1] row_mask:0xf bank_mask:0xf
	s_waitcnt lgkmcnt(0)
	s_nop 1
	v_add_f32_dpp v1, v1, v1 row_half_mirror row_mask:0xf bank_mask:0xf
	s_waitcnt lgkmcnt(0)
	s_nop 1
	v_add_f32_dpp v1, v1, v1 row_mirror row_mask:0xf bank_mask:0xf
	ds_bpermute_b32 v34, v147, v1
	s_waitcnt lgkmcnt(0)
	v_add_f32_e32 v1, v1, v34
	v_fmamk_f32 v1, v1, 0x3c000000, v208
	v_mul_f32_e32 v34, 0x4b800000, v1
	v_cmp_gt_f32_e32 vcc, s95, v1
	s_nop 1
	v_cndmask_b32_e32 v1, v1, v34, vcc
	v_rsq_f32_e32 v1, v1
	s_nop 0
	v_mul_f32_e32 v34, 0x45800000, v1
	v_cndmask_b32_e32 v1, v1, v34, vcc
	v_mul_f32_e32 v18, v18, v1
	s_nop 1
	v_mov_b32_dpp v50, v18 quad_perm:[1,0,3,2] row_mask:0xf bank_mask:0xf
	v_or_b32_e32 v34, s10, v140
	v_lshlrev_b64 v[34:35], 11, v[34:35]
	v_lshl_add_u64 v[34:35], v[196:197], 0, v[34:35]
	s_and_saveexec_b64 s[8:9], s[6:7]
	s_cbranch_execz .LBB0_223
	s_waitcnt lgkmcnt(0)
	v_cvt_pk_bf16_f32 v18, v18, v50
	global_store_dword v[34:35], v18, off
.LBB0_223:
	s_or_b64 exec, exec, s[8:9]
	v_mul_f32_e32 v18, v19, v1
	s_nop 1
	v_mov_b32_dpp v19, v18 quad_perm:[1,0,3,2] row_mask:0xf bank_mask:0xf
	s_and_saveexec_b64 s[8:9], s[6:7]
	s_cbranch_execz .LBB0_225
	s_waitcnt lgkmcnt(0)
	v_cvt_pk_bf16_f32 v18, v18, v19
	global_store_dword v[34:35], v18, off offset:64
.LBB0_225:
	s_or_b64 exec, exec, s[8:9]
	v_mul_f32_e32 v2, v2, v1
	s_nop 1
	v_mov_b32_dpp v18, v2 quad_perm:[1,0,3,2] row_mask:0xf bank_mask:0xf
	s_and_saveexec_b64 s[8:9], s[6:7]
	s_cbranch_execz .LBB0_227
	s_waitcnt lgkmcnt(0)
	v_cvt_pk_bf16_f32 v2, v2, v18
	global_store_dword v[34:35], v2, off offset:128
.LBB0_227:
	s_or_b64 exec, exec, s[8:9]
	v_mul_f32_e32 v1, v3, v1
	s_nop 1
	v_mov_b32_dpp v2, v1 quad_perm:[1,0,3,2] row_mask:0xf bank_mask:0xf
	s_and_saveexec_b64 s[8:9], s[6:7]
	s_cbranch_execz .LBB0_229
	s_waitcnt lgkmcnt(0)
	v_cvt_pk_bf16_f32 v1, v1, v2
	global_store_dword v[34:35], v1, off offset:192
.LBB0_229:
	s_or_b64 exec, exec, s[8:9]
	s_waitcnt lgkmcnt(0)
	ds_read2_b32 v[2:3], v167 offset1:32
	ds_read2_b32 v[34:35], v167 offset0:64 offset1:96
	v_mov_b32_e32 v18, v52
	v_mov_b32_e32 v19, v36
	v_mov_b32_e32 v50, v20
	s_waitcnt lgkmcnt(1)
	v_pk_fma_f32 v[18:19], v[18:19], v[92:93], v[2:3] op_sel_hi:[1,0,1] neg_lo:[0,0,1] neg_hi:[0,0,1]
	v_mov_b32_e32 v51, v4
	v_pk_mul_f32 v[94:95], v[18:19], v[18:19]
	s_waitcnt lgkmcnt(0)
	v_pk_fma_f32 v[2:3], v[50:51], v[92:93], v[34:35] op_sel_hi:[1,0,1] neg_lo:[0,0,1] neg_hi:[0,0,1]
	v_add_f32_e32 v1, v94, v95
	v_pk_mul_f32 v[34:35], v[2:3], v[2:3]
	s_nop 0
	v_add_f32_e32 v1, v1, v34
	v_add_f32_e32 v1, v1, v35
	v_mov_b32_e32 v35, s11
	v_or_b32_e32 v34, s10, v142
	v_lshlrev_b64 v[34:35], 11, v[34:35]
	v_lshl_add_u64 v[34:35], v[196:197], 0, v[34:35]
	s_waitcnt lgkmcnt(0)
	s_nop 1
	v_add_f32_dpp v1, v1, v1 quad_perm:[1,0,3,2] row_mask:0xf bank_mask:0xf
	s_waitcnt lgkmcnt(0)
	s_nop 1
	v_add_f32_dpp v1, v1, v1 quad_perm:[2,3,0,1] row_mask:0xf bank_mask:0xf
	s_waitcnt lgkmcnt(0)
	s_nop 1
	v_add_f32_dpp v1, v1, v1 row_half_mirror row_mask:0xf bank_mask:0xf
	s_waitcnt lgkmcnt(0)
	s_nop 1
	v_add_f32_dpp v1, v1, v1 row_mirror row_mask:0xf bank_mask:0xf
	ds_bpermute_b32 v4, v147, v1
	s_waitcnt lgkmcnt(0)
	v_add_f32_e32 v1, v1, v4
	v_fmamk_f32 v1, v1, 0x3c000000, v208
	v_mul_f32_e32 v4, 0x4b800000, v1
	v_cmp_gt_f32_e32 vcc, s95, v1
	s_nop 1
	v_cndmask_b32_e32 v1, v1, v4, vcc
	v_rsq_f32_e32 v1, v1
	s_nop 0
	v_mul_f32_e32 v4, 0x45800000, v1
	v_cndmask_b32_e32 v1, v1, v4, vcc
	v_mul_f32_e32 v4, v18, v1
	s_nop 1
	v_mov_b32_dpp v18, v4 quad_perm:[1,0,3,2] row_mask:0xf bank_mask:0xf
	s_and_saveexec_b64 s[8:9], s[6:7]
	s_cbranch_execz .LBB0_231
	s_waitcnt lgkmcnt(0)
	v_cvt_pk_bf16_f32 v4, v4, v18
	global_store_dword v[34:35], v4, off
.LBB0_231:
	s_or_b64 exec, exec, s[8:9]
	v_mul_f32_e32 v4, v19, v1
	s_waitcnt lgkmcnt(0)
	s_nop 1
	v_mov_b32_dpp v18, v4 quad_perm:[1,0,3,2] row_mask:0xf bank_mask:0xf
	s_and_saveexec_b64 s[8:9], s[6:7]
	s_cbranch_execz .LBB0_233
	s_waitcnt lgkmcnt(0)
	v_cvt_pk_bf16_f32 v4, v4, v18
	global_store_dword v[34:35], v4, off offset:64
.LBB0_233:
	s_or_b64 exec, exec, s[8:9]
	v_mul_f32_e32 v2, v2, v1
	s_nop 1
	v_mov_b32_dpp v4, v2 quad_perm:[1,0,3,2] row_mask:0xf bank_mask:0xf
	s_and_saveexec_b64 s[8:9], s[6:7]
	s_cbranch_execz .LBB0_235
	s_waitcnt lgkmcnt(0)
	v_cvt_pk_bf16_f32 v2, v2, v4
	global_store_dword v[34:35], v2, off offset:128

.LBB0_237:
	s_or_b64 exec, exec, s[8:9]
	s_waitcnt lgkmcnt(0)
	ds_read2_b32 v[2:3], v169 offset1:32
	ds_read2_b32 v[34:35], v169 offset0:64 offset1:96
	v_mov_b32_e32 v36, v53
	v_mov_b32_e32 v4, v21
	s_waitcnt lgkmcnt(1)
	v_pk_fma_f32 v[18:19], v[36:37], v[90:91], v[2:3] op_sel_hi:[1,0,1] neg_lo:[0,0,1] neg_hi:[0,0,1]
	s_waitcnt lgkmcnt(0)
	v_pk_fma_f32 v[2:3], v[4:5], v[90:91], v[34:35] op_sel_hi:[1,0,1] neg_lo:[0,0,1] neg_hi:[0,0,1]
	v_pk_mul_f32 v[4:5], v[18:19], v[18:19]
	v_pk_mul_f32 v[20:21], v[2:3], v[2:3]
	v_add_f32_e32 v1, v4, v5
	v_add_f32_e32 v1, v1, v20
	v_add_f32_e32 v1, v1, v21
	v_mov_b32_e32 v5, s11
	s_waitcnt lgkmcnt(0)
	s_nop 1
	v_add_f32_dpp v1, v1, v1 quad_perm:[1,0,3,2] row_mask:0xf bank_mask:0xf
	s_waitcnt lgkmcnt(0)
	s_nop 1
	v_add_f32_dpp v1, v1, v1 quad_perm:[2,3,0,1] row_mask:0xf bank_mask:0xf
	s_waitcnt lgkmcnt(0)
	s_nop 1
	v_add_f32_dpp v1, v1, v1 row_half_mirror row_mask:0xf bank_mask:0xf
	s_waitcnt lgkmcnt(0)
	s_nop 1
	v_add_f32_dpp v1, v1, v1 row_mirror row_mask:0xf bank_mask:0xf
	ds_bpermute_b32 v4, v147, v1
	s_waitcnt lgkmcnt(0)
	v_add_f32_e32 v1, v1, v4
	v_fmamk_f32 v1, v1, 0x3c000000, v208
	v_mul_f32_e32 v4, 0x4b800000, v1
	v_cmp_gt_f32_e32 vcc, s95, v1
	s_nop 1
	v_cndmask_b32_e32 v1, v1, v4, vcc
	v_rsq_f32_e32 v1, v1
	s_nop 0
	v_mul_f32_e32 v4, 0x45800000, v1
	v_cndmask_b32_e32 v1, v1, v4, vcc
	v_mul_f32_e32 v18, v18, v1
	s_nop 1
	v_mov_b32_dpp v20, v18 quad_perm:[1,0,3,2] row_mask:0xf bank_mask:0xf
	v_or_b32_e32 v4, s10, v144
	v_lshlrev_b64 v[4:5], 11, v[4:5]
	v_lshl_add_u64 v[4:5], v[196:197], 0, v[4:5]
	s_and_saveexec_b64 s[8:9], s[6:7]
	s_cbranch_execz .LBB0_239
	s_waitcnt lgkmcnt(0)
	v_cvt_pk_bf16_f32 v18, v18, v20
	global_store_dword v[4:5], v18, off
.LBB0_239:
	s_or_b64 exec, exec, s[8:9]
	v_mul_f32_e32 v18, v19, v1
	s_nop 1
	v_mov_b32_dpp v19, v18 quad_perm:[1,0,3,2] row_mask:0xf bank_mask:0xf
	s_and_saveexec_b64 s[8:9], s[6:7]
	s_cbranch_execz .LBB0_241
	s_waitcnt lgkmcnt(0)
	v_cvt_pk_bf16_f32 v18, v18, v19
	global_store_dword v[4:5], v18, off offset:64
.LBB0_241:
	s_or_b64 exec, exec, s[8:9]
	v_mul_f32_e32 v2, v2, v1
	s_nop 1
	v_mov_b32_dpp v18, v2 quad_perm:[1,0,3,2] row_mask:0xf bank_mask:0xf
	s_and_saveexec_b64 s[8:9], s[6:7]
	s_cbranch_execz .LBB0_243
	s_waitcnt lgkmcnt(0)
	v_cvt_pk_bf16_f32 v2, v2, v18
	global_store_dword v[4:5], v2, off offset:128
.LBB0_243:
	s_or_b64 exec, exec, s[8:9]
	v_mul_f32_e32 v1, v3, v1
	s_nop 1
	v_mov_b32_dpp v2, v1 quad_perm:[1,0,3,2] row_mask:0xf bank_mask:0xf
	s_and_saveexec_b64 s[8:9], s[6:7]
	s_cbranch_execz .LBB0_245
	s_waitcnt lgkmcnt(0)
	v_cvt_pk_bf16_f32 v1, v1, v2
	global_store_dword v[4:5], v1, off offset:192
.LBB0_245:
	s_or_b64 exec, exec, s[8:9]
	s_waitcnt lgkmcnt(0)
	ds_read2_b32 v[2:3], v202 offset1:32
	ds_read2_b32 v[18:19], v202 offset0:64 offset1:96
	v_mov_b32_e32 v4, v54
	v_mov_b32_e32 v5, v38
	v_mov_b32_e32 v20, v22
	s_waitcnt lgkmcnt(1)
	v_pk_fma_f32 v[4:5], v[4:5], v[88:89], v[2:3] op_sel_hi:[1,0,1] neg_lo:[0,0,1] neg_hi:[0,0,1]
	v_mov_b32_e32 v21, v6
	v_pk_mul_f32 v[34:35], v[4:5], v[4:5]
	s_waitcnt lgkmcnt(0)
	v_pk_fma_f32 v[2:3], v[20:21], v[88:89], v[18:19] op_sel_hi:[1,0,1] neg_lo:[0,0,1] neg_hi:[0,0,1]
	v_add_f32_e32 v1, v34, v35
	v_pk_mul_f32 v[18:19], v[2:3], v[2:3]
	s_nop 0
	v_add_f32_e32 v1, v1, v18
	v_add_f32_e32 v1, v1, v19
	v_mov_b32_e32 v19, s11
	v_or_b32_e32 v18, s10, v146
	v_lshlrev_b64 v[18:19], 11, v[18:19]
	v_lshl_add_u64 v[18:19], v[196:197], 0, v[18:19]
	s_waitcnt lgkmcnt(0)
	s_nop 1
	v_add_f32_dpp v1, v1, v1 quad_perm:[1,0,3,2] row_mask:0xf bank_mask:0xf
	s_waitcnt lgkmcnt(0)
	s_nop 1
	v_add_f32_dpp v1, v1, v1 quad_perm:[2,3,0,1] row_mask:0xf bank_mask:0xf
	s_waitcnt lgkmcnt(0)
	s_nop 1
	v_add_f32_dpp v1, v1, v1 row_half_mirror row_mask:0xf bank_mask:0xf
	s_waitcnt lgkmcnt(0)
	s_nop 1
	v_add_f32_dpp v1, v1, v1 row_mirror row_mask:0xf bank_mask:0xf
	ds_bpermute_b32 v6, v147, v1
	s_waitcnt lgkmcnt(0)
	v_add_f32_e32 v1, v1, v6
	v_fmamk_f32 v1, v1, 0x3c000000, v208
	v_mul_f32_e32 v6, 0x4b800000, v1
	v_cmp_gt_f32_e32 vcc, s95, v1
	s_nop 1
	v_cndmask_b32_e32 v1, v1, v6, vcc
	v_rsq_f32_e32 v1, v1
	s_nop 0
	v_mul_f32_e32 v6, 0x45800000, v1
	v_cndmask_b32_e32 v1, v1, v6, vcc
	v_mul_f32_e32 v4, v4, v1
	s_nop 1
	v_mov_b32_dpp v6, v4 quad_perm:[1,0,3,2] row_mask:0xf bank_mask:0xf
	s_and_saveexec_b64 s[8:9], s[6:7]
	s_cbranch_execz .LBB0_247
	s_waitcnt lgkmcnt(0)
	v_cvt_pk_bf16_f32 v4, v4, v6
	global_store_dword v[18:19], v4, off
.LBB0_247:
	s_or_b64 exec, exec, s[8:9]
	v_mul_f32_e32 v4, v5, v1
	s_nop 1
	v_mov_b32_dpp v5, v4 quad_perm:[1,0,3,2] row_mask:0xf bank_mask:0xf
	s_and_saveexec_b64 s[8:9], s[6:7]
	s_cbranch_execz .LBB0_249
	s_waitcnt lgkmcnt(0)
	v_cvt_pk_bf16_f32 v4, v4, v5
	global_store_dword v[18:19], v4, off offset:64
.LBB0_249:
	s_or_b64 exec, exec, s[8:9]
	v_mul_f32_e32 v2, v2, v1
	s_nop 1
	v_mov_b32_dpp v4, v2 quad_perm:[1,0,3,2] row_mask:0xf bank_mask:0xf
	s_and_saveexec_b64 s[8:9], s[6:7]
	s_cbranch_execz .LBB0_251
	s_waitcnt lgkmcnt(0)
	v_cvt_pk_bf16_f32 v2, v2, v4
	global_store_dword v[18:19], v2, off offset:128
.LBB0_251:
	s_or_b64 exec, exec, s[8:9]
	v_mul_f32_e32 v1, v3, v1
	s_nop 1
	v_mov_b32_dpp v2, v1 quad_perm:[1,0,3,2] row_mask:0xf bank_mask:0xf
	s_and_saveexec_b64 s[8:9], s[6:7]
	s_cbranch_execz .LBB0_253
	s_waitcnt lgkmcnt(0)
	v_cvt_pk_bf16_f32 v1, v1, v2
	global_store_dword v[18:19], v1, off offset:192
.LBB0_253:
	s_or_b64 exec, exec, s[8:9]
	s_waitcnt lgkmcnt(0)
	ds_read2_b32 v[2:3], v203 offset1:32
	ds_read2_b32 v[18:19], v203 offset0:64 offset1:96
	v_mov_b32_e32 v38, v55
	v_mov_b32_e32 v6, v23
	s_waitcnt lgkmcnt(1)
	v_pk_fma_f32 v[4:5], v[38:39], v[86:87], v[2:3] op_sel_hi:[1,0,1] neg_lo:[0,0,1] neg_hi:[0,0,1]
	s_waitcnt lgkmcnt(0)
	v_pk_fma_f32 v[2:3], v[6:7], v[86:87], v[18:19] op_sel_hi:[1,0,1] neg_lo:[0,0,1] neg_hi:[0,0,1]
	v_pk_mul_f32 v[6:7], v[4:5], v[4:5]
	v_pk_mul_f32 v[18:19], v[2:3], v[2:3]
	v_add_f32_e32 v1, v6, v7
	v_add_f32_e32 v1, v1, v18
	v_add_f32_e32 v1, v1, v19
	v_mov_b32_e32 v7, s11
	s_waitcnt lgkmcnt(0)
	s_nop 1
	v_add_f32_dpp v1, v1, v1 quad_perm:[1,0,3,2] row_mask:0xf bank_mask:0xf
	s_waitcnt lgkmcnt(0)
	s_nop 1
	v_add_f32_dpp v1, v1, v1 quad_perm:[2,3,0,1] row_mask:0xf bank_mask:0xf
	s_waitcnt lgkmcnt(0)
	s_nop 1
	v_add_f32_dpp v1, v1, v1 row_half_mirror row_mask:0xf bank_mask:0xf
	s_waitcnt lgkmcnt(0)
	s_nop 1
	v_add_f32_dpp v1, v1, v1 row_mirror row_mask:0xf bank_mask:0xf
	ds_bpermute_b32 v6, v147, v1
	s_waitcnt lgkmcnt(0)
	v_add_f32_e32 v1, v1, v6
	v_fmamk_f32 v1, v1, 0x3c000000, v208
	v_mul_f32_e32 v6, 0x4b800000, v1
	v_cmp_gt_f32_e32 vcc, s95, v1
	s_nop 1
	v_cndmask_b32_e32 v1, v1, v6, vcc
	v_rsq_f32_e32 v1, v1
	s_nop 0
	v_mul_f32_e32 v6, 0x45800000, v1
	v_cndmask_b32_e32 v1, v1, v6, vcc
	v_mul_f32_e32 v4, v4, v1
	s_nop 1
	v_mov_b32_dpp v18, v4 quad_perm:[1,0,3,2] row_mask:0xf bank_mask:0xf
	v_or_b32_e32 v6, s10, v148
	v_lshlrev_b64 v[6:7], 11, v[6:7]
	v_lshl_add_u64 v[6:7], v[196:197], 0, v[6:7]
	s_and_saveexec_b64 s[8:9], s[6:7]
	s_cbranch_execz .LBB0_255
	s_waitcnt lgkmcnt(0)
	v_cvt_pk_bf16_f32 v4, v4, v18
	global_store_dword v[6:7], v4, off
.LBB0_255:
	s_or_b64 exec, exec, s[8:9]
	v_mul_f32_e32 v4, v5, v1
	s_nop 1
	v_mov_b32_dpp v5, v4 quad_perm:[1,0,3,2] row_mask:0xf bank_mask:0xf
	s_and_saveexec_b64 s[8:9], s[6:7]
	s_cbranch_execz .LBB0_257
	s_waitcnt lgkmcnt(0)
	v_cvt_pk_bf16_f32 v4, v4, v5
	global_store_dword v[6:7], v4, off offset:64
.LBB0_257:
	s_or_b64 exec, exec, s[8:9]
	v_mul_f32_e32 v2, v2, v1
	s_nop 1
	v_mov_b32_dpp v4, v2 quad_perm:[1,0,3,2] row_mask:0xf bank_mask:0xf
	s_and_saveexec_b64 s[8:9], s[6:7]
	s_cbranch_execz .LBB0_259
	s_waitcnt lgkmcnt(0)
	v_cvt_pk_bf16_f32 v2, v2, v4
	global_store_dword v[6:7], v2, off offset:128
.LBB0_259:
	s_or_b64 exec, exec, s[8:9]
	v_mul_f32_e32 v1, v3, v1
	s_nop 1
	v_mov_b32_dpp v2, v1 quad_perm:[1,0,3,2] row_mask:0xf bank_mask:0xf
	s_and_saveexec_b64 s[8:9], s[6:7]
	s_cbranch_execz .LBB0_261
	s_waitcnt lgkmcnt(0)
	v_cvt_pk_bf16_f32 v1, v1, v2
	global_store_dword v[6:7], v1, off offset:192
.LBB0_261:
	s_or_b64 exec, exec, s[8:9]
	s_waitcnt lgkmcnt(0)
	ds_read2_b32 v[2:3], v204 offset1:32
	ds_read2_b32 v[6:7], v204 offset0:64 offset1:96
	v_mov_b32_e32 v4, v56
	v_mov_b32_e32 v5, v40
	v_mov_b32_e32 v18, v24
	s_waitcnt lgkmcnt(1)
	v_pk_fma_f32 v[4:5], v[4:5], v[84:85], v[2:3] op_sel_hi:[1,0,1] neg_lo:[0,0,1] neg_hi:[0,0,1]
	v_mov_b32_e32 v19, v8
	v_pk_mul_f32 v[20:21], v[4:5], v[4:5]
	s_waitcnt lgkmcnt(0)
	v_pk_fma_f32 v[2:3], v[18:19], v[84:85], v[6:7] op_sel_hi:[1,0,1] neg_lo:[0,0,1] neg_hi:[0,0,1]
	v_add_f32_e32 v1, v20, v21
	v_pk_mul_f32 v[6:7], v[2:3], v[2:3]
	s_nop 0
	v_add_f32_e32 v1, v1, v6
	v_add_f32_e32 v1, v1, v7
	v_mov_b32_e32 v7, s11
	s_waitcnt lgkmcnt(0)
	s_nop 1
	v_add_f32_dpp v1, v1, v1 quad_perm:[1,0,3,2] row_mask:0xf bank_mask:0xf
	s_waitcnt lgkmcnt(0)
	s_nop 1
	v_add_f32_dpp v1, v1, v1 quad_perm:[2,3,0,1] row_mask:0xf bank_mask:0xf
	s_waitcnt lgkmcnt(0)
	s_nop 1
	v_add_f32_dpp v1, v1, v1 row_half_mirror row_mask:0xf bank_mask:0xf
	s_waitcnt lgkmcnt(0)
	s_nop 1
	v_add_f32_dpp v1, v1, v1 row_mirror row_mask:0xf bank_mask:0xf
	ds_bpermute_b32 v6, v147, v1
	s_waitcnt lgkmcnt(0)
	v_add_f32_e32 v1, v1, v6
	v_fmamk_f32 v1, v1, 0x3c000000, v208
	v_mul_f32_e32 v6, 0x4b800000, v1
	v_cmp_gt_f32_e32 vcc, s95, v1
	s_nop 1
	v_cndmask_b32_e32 v1, v1, v6, vcc
	v_rsq_f32_e32 v1, v1
	s_nop 0
	v_mul_f32_e32 v6, 0x45800000, v1
	v_cndmask_b32_e32 v1, v1, v6, vcc
	v_mul_f32_e32 v4, v4, v1
	s_nop 1
	v_mov_b32_dpp v8, v4 quad_perm:[1,0,3,2] row_mask:0xf bank_mask:0xf
	v_or_b32_e32 v6, s10, v150
	v_lshlrev_b64 v[6:7], 11, v[6:7]
	v_lshl_add_u64 v[6:7], v[196:197], 0, v[6:7]
	s_and_saveexec_b64 s[8:9], s[6:7]
	s_cbranch_execz .LBB0_263
	s_waitcnt lgkmcnt(0)
	v_cvt_pk_bf16_f32 v4, v4, v8
	global_store_dword v[6:7], v4, off

.LBB0_269:
	s_or_b64 exec, exec, s[8:9]
	s_waitcnt lgkmcnt(0)
	ds_read2_b32 v[2:3], v205 offset1:32
	ds_read2_b32 v[6:7], v205 offset0:64 offset1:96
	v_mov_b32_e32 v40, v57
	v_mov_b32_e32 v8, v25
	s_waitcnt lgkmcnt(1)
	v_pk_fma_f32 v[4:5], v[40:41], v[82:83], v[2:3] op_sel_hi:[1,0,1] neg_lo:[0,0,1] neg_hi:[0,0,1]
	s_waitcnt lgkmcnt(0)
	v_pk_fma_f32 v[2:3], v[8:9], v[82:83], v[6:7] op_sel_hi:[1,0,1] neg_lo:[0,0,1] neg_hi:[0,0,1]
	v_pk_mul_f32 v[6:7], v[4:5], v[4:5]
	v_pk_mul_f32 v[8:9], v[2:3], v[2:3]
	v_add_f32_e32 v1, v6, v7
	v_add_f32_e32 v1, v1, v8
	v_add_f32_e32 v1, v1, v9
	v_mov_b32_e32 v7, s11
	s_waitcnt lgkmcnt(0)
	s_nop 1
	v_add_f32_dpp v1, v1, v1 quad_perm:[1,0,3,2] row_mask:0xf bank_mask:0xf
	s_waitcnt lgkmcnt(0)
	s_nop 1
	v_add_f32_dpp v1, v1, v1 quad_perm:[2,3,0,1] row_mask:0xf bank_mask:0xf
	s_waitcnt lgkmcnt(0)
	s_nop 1
	v_add_f32_dpp v1, v1, v1 row_half_mirror row_mask:0xf bank_mask:0xf
	s_waitcnt lgkmcnt(0)
	s_nop 1
	v_add_f32_dpp v1, v1, v1 row_mirror row_mask:0xf bank_mask:0xf
	ds_bpermute_b32 v6, v147, v1
	s_waitcnt lgkmcnt(0)
	v_add_f32_e32 v1, v1, v6
	v_fmamk_f32 v1, v1, 0x3c000000, v208
	v_mul_f32_e32 v6, 0x4b800000, v1
	v_cmp_gt_f32_e32 vcc, s95, v1
	s_nop 1
	v_cndmask_b32_e32 v1, v1, v6, vcc
	v_rsq_f32_e32 v1, v1
	s_nop 0
	v_mul_f32_e32 v6, 0x45800000, v1
	v_cndmask_b32_e32 v1, v1, v6, vcc
	v_mul_f32_e32 v4, v4, v1
	s_nop 1
	v_mov_b32_dpp v8, v4 quad_perm:[1,0,3,2] row_mask:0xf bank_mask:0xf
	v_or_b32_e32 v6, s10, v152
	v_lshlrev_b64 v[6:7], 11, v[6:7]
	v_lshl_add_u64 v[6:7], v[196:197], 0, v[6:7]
	s_and_saveexec_b64 s[8:9], s[6:7]
	s_cbranch_execz .LBB0_271
	s_waitcnt lgkmcnt(0)
	v_cvt_pk_bf16_f32 v4, v4, v8
	global_store_dword v[6:7], v4, off

.LBB0_277:
	s_or_b64 exec, exec, s[8:9]
	s_waitcnt lgkmcnt(0)
	ds_read2_b32 v[2:3], v216 offset1:32
	ds_read2_b32 v[6:7], v216 offset0:64 offset1:96
	v_mov_b32_e32 v4, v58
	v_mov_b32_e32 v5, v42
	v_mov_b32_e32 v8, v26
	s_waitcnt lgkmcnt(1)
	v_pk_fma_f32 v[4:5], v[4:5], v[80:81], v[2:3] op_sel_hi:[1,0,1] neg_lo:[0,0,1] neg_hi:[0,0,1]
	v_mov_b32_e32 v9, v10
	v_pk_mul_f32 v[18:19], v[4:5], v[4:5]
	s_waitcnt lgkmcnt(0)
	v_pk_fma_f32 v[2:3], v[8:9], v[80:81], v[6:7] op_sel_hi:[1,0,1] neg_lo:[0,0,1] neg_hi:[0,0,1]
	v_add_f32_e32 v1, v18, v19
	v_pk_mul_f32 v[6:7], v[2:3], v[2:3]
	s_nop 0
	v_add_f32_e32 v1, v1, v6
	v_add_f32_e32 v1, v1, v7
	v_mov_b32_e32 v7, s11
	s_waitcnt lgkmcnt(0)
	s_nop 1
	v_add_f32_dpp v1, v1, v1 quad_perm:[1,0,3,2] row_mask:0xf bank_mask:0xf
	s_waitcnt lgkmcnt(0)
	s_nop 1
	v_add_f32_dpp v1, v1, v1 quad_perm:[2,3,0,1] row_mask:0xf bank_mask:0xf
	s_waitcnt lgkmcnt(0)
	s_nop 1
	v_add_f32_dpp v1, v1, v1 row_half_mirror row_mask:0xf bank_mask:0xf
	s_waitcnt lgkmcnt(0)
	s_nop 1
	v_add_f32_dpp v1, v1, v1 row_mirror row_mask:0xf bank_mask:0xf
	ds_bpermute_b32 v6, v147, v1
	s_waitcnt lgkmcnt(0)
	v_add_f32_e32 v1, v1, v6
	v_fmamk_f32 v1, v1, 0x3c000000, v208
	v_mul_f32_e32 v6, 0x4b800000, v1
	v_cmp_gt_f32_e32 vcc, s95, v1
	s_nop 1
	v_cndmask_b32_e32 v1, v1, v6, vcc
	v_rsq_f32_e32 v1, v1
	s_nop 0
	v_mul_f32_e32 v6, 0x45800000, v1
	v_cndmask_b32_e32 v1, v1, v6, vcc
	v_mul_f32_e32 v4, v4, v1
	s_nop 1
	v_mov_b32_dpp v8, v4 quad_perm:[1,0,3,2] row_mask:0xf bank_mask:0xf
	v_or_b32_e32 v6, s10, v154
	v_lshlrev_b64 v[6:7], 11, v[6:7]
	v_lshl_add_u64 v[6:7], v[196:197], 0, v[6:7]
	s_and_saveexec_b64 s[8:9], s[6:7]
	s_cbranch_execz .LBB0_279
	s_waitcnt lgkmcnt(0)
	v_cvt_pk_bf16_f32 v4, v4, v8
	global_store_dword v[6:7], v4, off

.LBB0_285:
	s_or_b64 exec, exec, s[8:9]
	s_waitcnt lgkmcnt(0)
	ds_read2_b32 v[2:3], v217 offset1:32
	ds_read2_b32 v[6:7], v217 offset0:64 offset1:96
	v_mov_b32_e32 v42, v59
	v_mov_b32_e32 v10, v27
	s_waitcnt lgkmcnt(1)
	v_pk_fma_f32 v[4:5], v[42:43], v[76:77], v[2:3] op_sel_hi:[1,0,1] neg_lo:[0,0,1] neg_hi:[0,0,1]
	s_waitcnt lgkmcnt(0)
	v_pk_fma_f32 v[2:3], v[10:11], v[76:77], v[6:7] op_sel_hi:[1,0,1] neg_lo:[0,0,1] neg_hi:[0,0,1]
	v_pk_mul_f32 v[6:7], v[4:5], v[4:5]
	v_pk_mul_f32 v[8:9], v[2:3], v[2:3]
	v_add_f32_e32 v1, v6, v7
	v_add_f32_e32 v1, v1, v8
	v_add_f32_e32 v1, v1, v9
	v_mov_b32_e32 v7, s11
	s_waitcnt lgkmcnt(0)
	s_nop 1
	v_add_f32_dpp v1, v1, v1 quad_perm:[1,0,3,2] row_mask:0xf bank_mask:0xf
	s_waitcnt lgkmcnt(0)
	s_nop 1
	v_add_f32_dpp v1, v1, v1 quad_perm:[2,3,0,1] row_mask:0xf bank_mask:0xf
	s_waitcnt lgkmcnt(0)
	s_nop 1
	v_add_f32_dpp v1, v1, v1 row_half_mirror row_mask:0xf bank_mask:0xf
	s_waitcnt lgkmcnt(0)
	s_nop 1
	v_add_f32_dpp v1, v1, v1 row_mirror row_mask:0xf bank_mask:0xf
	ds_bpermute_b32 v6, v147, v1
	s_waitcnt lgkmcnt(0)
	v_add_f32_e32 v1, v1, v6
	v_fmamk_f32 v1, v1, 0x3c000000, v208
	v_mul_f32_e32 v6, 0x4b800000, v1
	v_cmp_gt_f32_e32 vcc, s95, v1
	s_nop 1
	v_cndmask_b32_e32 v1, v1, v6, vcc
	v_rsq_f32_e32 v1, v1
	s_nop 0
	v_mul_f32_e32 v6, 0x45800000, v1
	v_cndmask_b32_e32 v1, v1, v6, vcc
	v_mul_f32_e32 v4, v4, v1
	s_nop 1
	v_mov_b32_dpp v8, v4 quad_perm:[1,0,3,2] row_mask:0xf bank_mask:0xf
	v_or_b32_e32 v6, s10, v156
	v_lshlrev_b64 v[6:7], 11, v[6:7]
	v_lshl_add_u64 v[6:7], v[196:197], 0, v[6:7]
	s_and_saveexec_b64 s[8:9], s[6:7]
	s_cbranch_execz .LBB0_287
	s_waitcnt lgkmcnt(0)
	v_cvt_pk_bf16_f32 v4, v4, v8
	global_store_dword v[6:7], v4, off

.LBB0_293:
	s_or_b64 exec, exec, s[8:9]
	s_waitcnt lgkmcnt(0)
	ds_read2_b32 v[2:3], v218 offset1:32
	ds_read2_b32 v[6:7], v218 offset0:64 offset1:96
	v_mov_b32_e32 v4, v60
	v_mov_b32_e32 v5, v44
	v_mov_b32_e32 v8, v28
	s_waitcnt lgkmcnt(1)
	v_pk_fma_f32 v[4:5], v[4:5], v[72:73], v[2:3] op_sel_hi:[1,0,1] neg_lo:[0,0,1] neg_hi:[0,0,1]
	v_mov_b32_e32 v9, v12
	v_pk_mul_f32 v[10:11], v[4:5], v[4:5]
	s_waitcnt lgkmcnt(0)
	v_pk_fma_f32 v[2:3], v[8:9], v[72:73], v[6:7] op_sel_hi:[1,0,1] neg_lo:[0,0,1] neg_hi:[0,0,1]
	v_add_f32_e32 v1, v10, v11
	v_pk_mul_f32 v[6:7], v[2:3], v[2:3]
	s_nop 0
	v_add_f32_e32 v1, v1, v6
	v_add_f32_e32 v1, v1, v7
	v_mov_b32_e32 v7, s11
	s_waitcnt lgkmcnt(0)
	s_nop 1
	v_add_f32_dpp v1, v1, v1 quad_perm:[1,0,3,2] row_mask:0xf bank_mask:0xf
	s_waitcnt lgkmcnt(0)
	s_nop 1
	v_add_f32_dpp v1, v1, v1 quad_perm:[2,3,0,1] row_mask:0xf bank_mask:0xf
	s_waitcnt lgkmcnt(0)
	s_nop 1
	v_add_f32_dpp v1, v1, v1 row_half_mirror row_mask:0xf bank_mask:0xf
	s_waitcnt lgkmcnt(0)
	s_nop 1
	v_add_f32_dpp v1, v1, v1 row_mirror row_mask:0xf bank_mask:0xf
	ds_bpermute_b32 v6, v147, v1
	s_waitcnt lgkmcnt(0)
	v_add_f32_e32 v1, v1, v6
	v_fmamk_f32 v1, v1, 0x3c000000, v208
	v_mul_f32_e32 v6, 0x4b800000, v1
	v_cmp_gt_f32_e32 vcc, s95, v1
	s_nop 1
	v_cndmask_b32_e32 v1, v1, v6, vcc
	v_rsq_f32_e32 v1, v1
	s_nop 0
	v_mul_f32_e32 v6, 0x45800000, v1
	v_cndmask_b32_e32 v1, v1, v6, vcc
	v_mul_f32_e32 v4, v4, v1
	s_nop 1
	v_mov_b32_dpp v8, v4 quad_perm:[1,0,3,2] row_mask:0xf bank_mask:0xf
	v_or_b32_e32 v6, s10, v158
	v_lshlrev_b64 v[6:7], 11, v[6:7]
	v_lshl_add_u64 v[6:7], v[196:197], 0, v[6:7]
	s_and_saveexec_b64 s[8:9], s[6:7]
	s_cbranch_execz .LBB0_295
	s_waitcnt lgkmcnt(0)
	v_cvt_pk_bf16_f32 v4, v4, v8
	global_store_dword v[6:7], v4, off

.LBB0_301:
	s_or_b64 exec, exec, s[8:9]
	s_waitcnt lgkmcnt(0)
	ds_read2_b32 v[2:3], v219 offset1:32
	ds_read2_b32 v[6:7], v219 offset0:64 offset1:96
	v_mov_b32_e32 v44, v61
	v_mov_b32_e32 v12, v29
	s_waitcnt lgkmcnt(1)
	v_pk_fma_f32 v[4:5], v[44:45], v[70:71], v[2:3] op_sel_hi:[1,0,1] neg_lo:[0,0,1] neg_hi:[0,0,1]
	s_waitcnt lgkmcnt(0)
	v_pk_fma_f32 v[2:3], v[12:13], v[70:71], v[6:7] op_sel_hi:[1,0,1] neg_lo:[0,0,1] neg_hi:[0,0,1]
	v_pk_mul_f32 v[6:7], v[4:5], v[4:5]
	v_pk_mul_f32 v[8:9], v[2:3], v[2:3]
	v_add_f32_e32 v1, v6, v7
	v_add_f32_e32 v1, v1, v8
	v_add_f32_e32 v1, v1, v9
	v_mov_b32_e32 v7, s11
	s_waitcnt lgkmcnt(0)
	s_nop 1
	v_add_f32_dpp v1, v1, v1 quad_perm:[1,0,3,2] row_mask:0xf bank_mask:0xf
	s_waitcnt lgkmcnt(0)
	s_nop 1
	v_add_f32_dpp v1, v1, v1 quad_perm:[2,3,0,1] row_mask:0xf bank_mask:0xf
	s_waitcnt lgkmcnt(0)
	s_nop 1
	v_add_f32_dpp v1, v1, v1 row_half_mirror row_mask:0xf bank_mask:0xf
	s_waitcnt lgkmcnt(0)
	s_nop 1
	v_add_f32_dpp v1, v1, v1 row_mirror row_mask:0xf bank_mask:0xf
	ds_bpermute_b32 v6, v147, v1
	s_waitcnt lgkmcnt(0)
	v_add_f32_e32 v1, v1, v6
	v_fmamk_f32 v1, v1, 0x3c000000, v208
	v_mul_f32_e32 v6, 0x4b800000, v1
	v_cmp_gt_f32_e32 vcc, s95, v1
	s_nop 1
	v_cndmask_b32_e32 v1, v1, v6, vcc
	v_rsq_f32_e32 v1, v1
	s_nop 0
	v_mul_f32_e32 v6, 0x45800000, v1
	v_cndmask_b32_e32 v1, v1, v6, vcc
	v_mul_f32_e32 v4, v4, v1
	s_nop 1
	v_mov_b32_dpp v8, v4 quad_perm:[1,0,3,2] row_mask:0xf bank_mask:0xf
	v_or_b32_e32 v6, s10, v160
	v_lshlrev_b64 v[6:7], 11, v[6:7]
	v_lshl_add_u64 v[6:7], v[196:197], 0, v[6:7]
	s_and_saveexec_b64 s[8:9], s[6:7]
	s_cbranch_execz .LBB0_303
	s_waitcnt lgkmcnt(0)
	v_cvt_pk_bf16_f32 v4, v4, v8
	global_store_dword v[6:7], v4, off

.LBB0_309:
	s_or_b64 exec, exec, s[8:9]
	s_waitcnt lgkmcnt(0)
	ds_read2_b32 v[2:3], v220 offset1:32
	ds_read2_b32 v[6:7], v220 offset0:64 offset1:96
	v_mov_b32_e32 v4, v62
	v_mov_b32_e32 v5, v46
	v_mov_b32_e32 v8, v30
	s_waitcnt lgkmcnt(1)
	v_pk_fma_f32 v[4:5], v[4:5], v[78:79], v[2:3] op_sel_hi:[1,0,1] neg_lo:[0,0,1] neg_hi:[0,0,1]
	v_mov_b32_e32 v9, v14
	v_pk_mul_f32 v[10:11], v[4:5], v[4:5]
	s_waitcnt lgkmcnt(0)
	v_pk_fma_f32 v[2:3], v[8:9], v[78:79], v[6:7] op_sel_hi:[1,0,1] neg_lo:[0,0,1] neg_hi:[0,0,1]
	v_add_f32_e32 v1, v10, v11
	v_pk_mul_f32 v[6:7], v[2:3], v[2:3]
	s_nop 0
	v_add_f32_e32 v1, v1, v6
	v_add_f32_e32 v1, v1, v7
	v_mov_b32_e32 v7, s11
	s_waitcnt lgkmcnt(0)
	s_nop 1
	v_add_f32_dpp v1, v1, v1 quad_perm:[1,0,3,2] row_mask:0xf bank_mask:0xf
	s_waitcnt lgkmcnt(0)
	s_nop 1
	v_add_f32_dpp v1, v1, v1 quad_perm:[2,3,0,1] row_mask:0xf bank_mask:0xf
	s_waitcnt lgkmcnt(0)
	s_nop 1
	v_add_f32_dpp v1, v1, v1 row_half_mirror row_mask:0xf bank_mask:0xf
	s_waitcnt lgkmcnt(0)
	s_nop 1
	v_add_f32_dpp v1, v1, v1 row_mirror row_mask:0xf bank_mask:0xf
	ds_bpermute_b32 v6, v147, v1
	s_waitcnt lgkmcnt(0)
	v_add_f32_e32 v1, v1, v6
	v_fmamk_f32 v1, v1, 0x3c000000, v208
	v_mul_f32_e32 v6, 0x4b800000, v1
	v_cmp_gt_f32_e32 vcc, s95, v1
	s_nop 1
	v_cndmask_b32_e32 v1, v1, v6, vcc
	v_rsq_f32_e32 v1, v1
	s_nop 0
	v_mul_f32_e32 v6, 0x45800000, v1
	v_cndmask_b32_e32 v1, v1, v6, vcc
	v_mul_f32_e32 v4, v4, v1
	s_nop 1
	v_mov_b32_dpp v8, v4 quad_perm:[1,0,3,2] row_mask:0xf bank_mask:0xf
	v_or_b32_e32 v6, s10, v162
	v_lshlrev_b64 v[6:7], 11, v[6:7]
	v_lshl_add_u64 v[6:7], v[196:197], 0, v[6:7]
	s_and_saveexec_b64 s[8:9], s[6:7]
	s_cbranch_execz .LBB0_311
	s_waitcnt lgkmcnt(0)
	v_cvt_pk_bf16_f32 v4, v4, v8
	global_store_dword v[6:7], v4, off

.LBB0_317:
	s_or_b64 exec, exec, s[8:9]
	s_waitcnt lgkmcnt(0)
	ds_read2_b32 v[2:3], v221 offset1:32
	ds_read2_b32 v[6:7], v221 offset0:64 offset1:96
	v_mov_b32_e32 v46, v63
	v_mov_b32_e32 v14, v31
	s_waitcnt lgkmcnt(1)
	v_pk_fma_f32 v[4:5], v[46:47], v[74:75], v[2:3] op_sel_hi:[1,0,1] neg_lo:[0,0,1] neg_hi:[0,0,1]
	s_waitcnt lgkmcnt(0)
	v_pk_fma_f32 v[2:3], v[14:15], v[74:75], v[6:7] op_sel_hi:[1,0,1] neg_lo:[0,0,1] neg_hi:[0,0,1]
	v_pk_mul_f32 v[6:7], v[4:5], v[4:5]
	v_pk_mul_f32 v[8:9], v[2:3], v[2:3]
	v_add_f32_e32 v1, v6, v7
	v_add_f32_e32 v1, v1, v8
	v_add_f32_e32 v1, v1, v9
	v_mov_b32_e32 v7, s11
	s_waitcnt lgkmcnt(0)
	s_nop 1
	v_add_f32_dpp v1, v1, v1 quad_perm:[1,0,3,2] row_mask:0xf bank_mask:0xf
	s_waitcnt lgkmcnt(0)
	s_nop 1
	v_add_f32_dpp v1, v1, v1 quad_perm:[2,3,0,1] row_mask:0xf bank_mask:0xf
	s_waitcnt lgkmcnt(0)
	s_nop 1
	v_add_f32_dpp v1, v1, v1 row_half_mirror row_mask:0xf bank_mask:0xf
	s_waitcnt lgkmcnt(0)
	s_nop 1
	v_add_f32_dpp v1, v1, v1 row_mirror row_mask:0xf bank_mask:0xf
	ds_bpermute_b32 v6, v147, v1
	s_waitcnt lgkmcnt(0)
	v_add_f32_e32 v1, v1, v6
	v_fmamk_f32 v1, v1, 0x3c000000, v208
	v_mul_f32_e32 v6, 0x4b800000, v1
	v_cmp_gt_f32_e32 vcc, s95, v1
	s_nop 1
	v_cndmask_b32_e32 v1, v1, v6, vcc
	v_rsq_f32_e32 v1, v1
	s_nop 0
	v_mul_f32_e32 v6, 0x45800000, v1
	v_cndmask_b32_e32 v1, v1, v6, vcc
	v_mul_f32_e32 v4, v4, v1
	s_nop 1
	v_mov_b32_dpp v8, v4 quad_perm:[1,0,3,2] row_mask:0xf bank_mask:0xf
	v_or_b32_e32 v6, s10, v164
	v_lshlrev_b64 v[6:7], 11, v[6:7]
	v_lshl_add_u64 v[6:7], v[196:197], 0, v[6:7]
	s_and_saveexec_b64 s[8:9], s[6:7]
	s_cbranch_execz .LBB0_319
	s_waitcnt lgkmcnt(0)
	v_cvt_pk_bf16_f32 v4, v4, v8
	global_store_dword v[6:7], v4, off

.LBB0_325:
	s_or_b64 exec, exec, s[8:9]
	s_waitcnt lgkmcnt(0)
	ds_read2_b32 v[2:3], v222 offset1:32
	ds_read2_b32 v[6:7], v222 offset0:64 offset1:96
	v_mov_b32_e32 v4, v64
	v_mov_b32_e32 v5, v48
	v_mov_b32_e32 v8, v32
	s_waitcnt lgkmcnt(1)
	v_pk_fma_f32 v[4:5], v[4:5], v[68:69], v[2:3] op_sel_hi:[1,0,1] neg_lo:[0,0,1] neg_hi:[0,0,1]
	v_mov_b32_e32 v9, v16
	v_pk_mul_f32 v[10:11], v[4:5], v[4:5]
	s_waitcnt lgkmcnt(0)
	v_pk_fma_f32 v[2:3], v[8:9], v[68:69], v[6:7] op_sel_hi:[1,0,1] neg_lo:[0,0,1] neg_hi:[0,0,1]
	v_add_f32_e32 v1, v10, v11
	v_pk_mul_f32 v[6:7], v[2:3], v[2:3]
	s_nop 0
	v_add_f32_e32 v1, v1, v6
	v_add_f32_e32 v1, v1, v7
	v_mov_b32_e32 v7, s11
	s_waitcnt lgkmcnt(0)
	s_nop 1
	v_add_f32_dpp v1, v1, v1 quad_perm:[1,0,3,2] row_mask:0xf bank_mask:0xf
	s_waitcnt lgkmcnt(0)
	s_nop 1
	v_add_f32_dpp v1, v1, v1 quad_perm:[2,3,0,1] row_mask:0xf bank_mask:0xf
	s_waitcnt lgkmcnt(0)
	s_nop 1
	v_add_f32_dpp v1, v1, v1 row_half_mirror row_mask:0xf bank_mask:0xf
	s_waitcnt lgkmcnt(0)
	s_nop 1
	v_add_f32_dpp v1, v1, v1 row_mirror row_mask:0xf bank_mask:0xf
	ds_bpermute_b32 v6, v147, v1
	s_waitcnt lgkmcnt(0)
	v_add_f32_e32 v1, v1, v6
	v_fmamk_f32 v1, v1, 0x3c000000, v208
	v_mul_f32_e32 v6, 0x4b800000, v1
	v_cmp_gt_f32_e32 vcc, s95, v1
	s_nop 1
	v_cndmask_b32_e32 v1, v1, v6, vcc
	v_rsq_f32_e32 v1, v1
	s_nop 0
	v_mul_f32_e32 v6, 0x45800000, v1
	v_cndmask_b32_e32 v1, v1, v6, vcc
	v_mul_f32_e32 v4, v4, v1
	s_nop 1
	v_mov_b32_dpp v8, v4 quad_perm:[1,0,3,2] row_mask:0xf bank_mask:0xf
	v_or_b32_e32 v6, s10, v166
	v_lshlrev_b64 v[6:7], 11, v[6:7]
	v_lshl_add_u64 v[6:7], v[196:197], 0, v[6:7]
	s_and_saveexec_b64 s[8:9], s[6:7]
	s_cbranch_execz .LBB0_327
	s_waitcnt lgkmcnt(0)
	v_cvt_pk_bf16_f32 v4, v4, v8
	global_store_dword v[6:7], v4, off

.LBB0_333:
	s_or_b64 exec, exec, s[8:9]
	s_waitcnt lgkmcnt(0)
	ds_read2_b32 v[2:3], v223 offset1:32
	ds_read2_b32 v[4:5], v223 offset0:64 offset1:96
	v_mov_b32_e32 v48, v65
	v_mov_b32_e32 v16, v33
	s_waitcnt lgkmcnt(1)
	v_pk_fma_f32 v[2:3], v[48:49], v[66:67], v[2:3] op_sel_hi:[1,0,1] neg_lo:[0,0,1] neg_hi:[0,0,1]
	s_nop 0
	v_pk_mul_f32 v[6:7], v[2:3], v[2:3]
	s_waitcnt lgkmcnt(0)
	v_pk_fma_f32 v[4:5], v[16:17], v[66:67], v[4:5] op_sel_hi:[1,0,1] neg_lo:[0,0,1] neg_hi:[0,0,1]
	v_add_f32_e32 v1, v6, v7
	v_pk_mul_f32 v[8:9], v[4:5], v[4:5]
	v_mov_b32_e32 v7, s11
	v_add_f32_e32 v1, v1, v8
	v_add_f32_e32 v1, v1, v9
	s_waitcnt lgkmcnt(0)
	s_nop 1
	v_add_f32_dpp v1, v1, v1 quad_perm:[1,0,3,2] row_mask:0xf bank_mask:0xf
	s_waitcnt lgkmcnt(0)
	s_nop 1
	v_add_f32_dpp v1, v1, v1 quad_perm:[2,3,0,1] row_mask:0xf bank_mask:0xf
	s_waitcnt lgkmcnt(0)
	s_nop 1
	v_add_f32_dpp v1, v1, v1 row_half_mirror row_mask:0xf bank_mask:0xf
	s_waitcnt lgkmcnt(0)
	s_nop 1
	v_add_f32_dpp v1, v1, v1 row_mirror row_mask:0xf bank_mask:0xf
	ds_bpermute_b32 v6, v147, v1
	s_waitcnt lgkmcnt(0)
	v_add_f32_e32 v1, v1, v6
	v_fmamk_f32 v1, v1, 0x3c000000, v208
	v_cmp_gt_f32_e32 vcc, s95, v1
	v_mul_f32_e32 v6, 0x4b800000, v1
	s_nop 0
	v_cndmask_b32_e32 v1, v1, v6, vcc
	v_rsq_f32_e32 v1, v1
	s_nop 0
	v_mul_f32_e32 v6, 0x45800000, v1
	v_cndmask_b32_e32 v1, v1, v6, vcc
	v_mul_f32_e32 v2, v2, v1
	s_nop 1
	v_mov_b32_dpp v8, v2 quad_perm:[1,0,3,2] row_mask:0xf bank_mask:0xf
	v_or_b32_e32 v6, s10, v168
	v_lshlrev_b64 v[6:7], 11, v[6:7]
	v_lshl_add_u64 v[6:7], v[196:197], 0, v[6:7]
	s_and_saveexec_b64 s[8:9], s[6:7]
	s_cbranch_execz .LBB0_335
	s_waitcnt lgkmcnt(0)
	v_cvt_pk_bf16_f32 v2, v2, v8
	global_store_dword v[6:7], v2, off
.LBB0_335:
	s_or_b64 exec, exec, s[8:9]
	v_mul_f32_e32 v2, v3, v1
	s_nop 1
	v_mov_b32_dpp v3, v2 quad_perm:[1,0,3,2] row_mask:0xf bank_mask:0xf
	s_and_saveexec_b64 s[8:9], s[6:7]
	s_cbranch_execz .LBB0_337
	s_waitcnt lgkmcnt(0)
	v_cvt_pk_bf16_f32 v2, v2, v3
	global_store_dword v[6:7], v2, off offset:64
.LBB0_337:
	s_or_b64 exec, exec, s[8:9]
	v_mul_f32_e32 v2, v4, v1
	s_waitcnt lgkmcnt(0)
	s_nop 1
	v_mov_b32_dpp v3, v2 quad_perm:[1,0,3,2] row_mask:0xf bank_mask:0xf
	s_and_saveexec_b64 s[8:9], s[6:7]
	s_cbranch_execz .LBB0_339
	s_waitcnt lgkmcnt(0)
	v_cvt_pk_bf16_f32 v2, v2, v3
	global_store_dword v[6:7], v2, off offset:128
.LBB0_339:
	s_or_b64 exec, exec, s[8:9]
	v_mul_f32_e32 v1, v5, v1
	s_nop 1
	v_mov_b32_dpp v2, v1 quad_perm:[1,0,3,2] row_mask:0xf bank_mask:0xf
	s_and_saveexec_b64 s[8:9], s[6:7]
	s_cbranch_execz .LBB0_160
	s_waitcnt lgkmcnt(0)
	v_cvt_pk_bf16_f32 v1, v1, v2
	global_store_dword v[6:7], v1, off offset:192
	s_branch .LBB0_160
